# longest-first attention queue with a longer descending tail: chunks 7..0 (8 down to 1 key tiles) served last
# baseline (speedup 1.0000x reference)
.LBB0_801:
	s_or_b64 exec, exec, s[12:13]
	v_readfirstlane_b32 s43, v0
	s_cmpk_gt_i32 s43, 0x3fff
	s_mov_b64 s[12:13], -1
	s_cbranch_scc1 .LBB0_796
	s_cmpk_lt_u32 s43, 0x3000
	s_cbranch_scc0 .Lq_tail
	s_mul_hi_u32 s12, s43, 0x5555556
	s_mul_i32 s13, s12, 48
	s_sub_i32 s13, s43, s13
	s_add_i32 s13, s13, 16
	s_lshl_b32 s12, s12, 6
	s_or_b32 s43, s12, s13
	s_branch .Lq_mapped
.Lq_tail:
	s_sub_i32 s13, s43, 0x3000
	s_bfe_u32 s12, s13, 0x80001
	s_lshr_b32 s14, s13, 9
	s_sub_i32 s14, 7, s14
	s_and_b32 s13, s13, 1
	s_lshl_b32 s12, s12, 6
	s_lshl_b32 s14, s14, 1
	s_or_b32 s12, s12, s14
	s_or_b32 s43, s12, s13
